# attention: DPP row-rotate max instead of ds_swizzle, skip band-mask materialisation on unmasked tiles; conv units dealt from the other end
# speedup vs baseline: 1.0068x; 1.0068x over previous
; #define LAS __attribute__((address_space(3)))
;     __device__ __forceinline__ const float* in(int i) const { return (const float*)(const __attribute__((address_space(1))) float*)get(i); }
;     __device__ __forceinline__ unsigned char* ws() const { return (unsigned char*)(__attribute__((address_space(1))) unsigned char*)get(35); }
; __device__ __forceinline__ void conv_unit(const PA& a, int l, int un, LAS unsigned char* lds, int tid) {
;     LAS float* ybuf = (LAS float*)lds;
;     const bf16* YB = (const bf16*)(a.ws() + WS_YB); bf16* BRB = (bf16*)(a.ws() + WS_BR) + (size_t)NTOK * 512;
;     const int lane = tid & 63, w = tid >> 6;
;     const int t0 = un * 32; int s0, s1;
;     if (t0 < NLAT) { s0 = t0 & ~(SEQ - 1); s1 = s0 + SEQ; } else { s0 = NLAT + ((t0 - NLAT) & ~(CTXL - 1)); s1 = s0 + CTXL; }
;     const int cp = tid & 255, half = tid >> 8, rb = t0 + half * 16 - 15;
;     const float* cw = a.in(I_CW) + (size_t)l * 31 * 512 + 2 * cp;
; __global__ void __launch_bounds__(512, 2) mega_fwd(Args args) {
;     ...
;             { PH_BEGIN for (int u = bid; u < NTOK / 32; u += G) conv_unit(a, l, u, ldsL, tid); }
.LBB0_817:
	s_sub_i32 s10, s92, s81
	s_add_i32 s10, s10, -1
	s_mov_b32 s11, s92
	s_mov_b32 s0, s93
	v_mbcnt_lo_u32_b32 v0, -1, 0
	v_mbcnt_hi_u32_b32 v0, -1, v0
	s_cmpk_gt_i32 s10, 0x41f
	v_lshl_or_b32 v0, s0, 6, v0
	s_waitcnt lgkmcnt(0)
	v_mov_b32 v1, 0
	s_nop 0
	v_add_u32_e32 v1, s79, v1
	ds_read_b32 v2, v1 offset:280
	ds_read_b32 v1, v1 offset:284
	s_cbranch_scc1 .LBB0_822
	s_waitcnt lgkmcnt(1)
	v_lshlrev_b32_e32 v2, 1, v0
	s_waitcnt lgkmcnt(0)
	v_ashrrev_i32_e32 v1, 4, v0
	v_and_b32_e32 v48, 0x1fe, v2
	v_ashrrev_i32_e32 v2, 6, v0
	v_lshlrev_b32_e32 v0, 3, v0
	v_and_b32_e32 v49, -16, v1
	v_mov_b32_e32 v5, 0x7800
	v_and_b32_e32 v50, 0x1f8, v0
	s_lshl_b32 s62, s96, 9
	v_lshl_add_u32 v3, v48, 2, 0
	v_lshlrev_b32_e32 v4, 11, v49
	v_lshl_or_b32 v1, v1, 11, v5
	v_lshlrev_b32_e32 v0, 13, v2
	v_lshlrev_b32_e32 v5, 2, v50
	v_add3_u32 v51, 0, v0, v5
	v_lshlrev_b32_e32 v142, 2, v2
	s_lshl_b32 s12, s10, 5
	s_lshl_b32 s13, s11, 5
	s_lshl_b64 s[4:5], s[62:63], 2
	v_add_u32_e32 v143, v3, v4
	v_add_u32_e32 v144, v3, v1
	s_branch .LBB0_820

; __device__ __forceinline__ void attn_unit(const PA& a, int l, int unit, LAS unsigned char* lds, int tid) {
;     ...
;                 if (t == 0 || t == 2) {
; #pragma unroll
;                     for (int nt = 0; nt < 8; ++nt)
; #pragma unroll
;                         for (int j = 0; j < 4; ++j) { const int qi = 16 * w + kg * 4 + j, ki = nt * 16 + fr; const bool ok = (t == 0) ? (qi <= ki) : (ki <= qi); if (!ok) s[h][nt][j] = -1e30f; } }
.LBB0_846:
	v_readlane_b32 s0, v254, 55
	v_readlane_b32 s1, v254, 56
	s_andn2_b64 vcc, exec, s[46:47]
	s_cbranch_vccnz .LBB0_848
	v_cndmask_b32_e64 v242, 0, 1, s[56:57]
	v_cndmask_b32_e64 v182, 0, 1, s[0:1]
	v_readlane_b32 s0, v254, 57
	v_readlane_b32 s1, v254, 58
	v_cndmask_b32_e64 v243, 0, 1, s[60:61]
	v_cndmask_b32_e64 v240, 0, 1, s[66:67]
	v_cndmask_b32_e64 v179, 0, 1, s[0:1]
	v_readlane_b32 s0, v254, 59
	v_readlane_b32 s1, v254, 60
	v_cndmask_b32_e64 v241, 0, 1, s[68:69]
	v_cndmask_b32_e64 v238, 0, 1, s[70:71]
	v_cndmask_b32_e64 v192, 0, 1, s[0:1]
	v_readlane_b32 s0, v254, 61
	v_readlane_b32 s1, v254, 62
	v_cndmask_b32_e64 v239, 0, 1, s[72:73]
	v_cndmask_b32_e64 v236, 0, 1, s[74:75]
	v_cndmask_b32_e64 v187, 0, 1, s[0:1]
	v_readlane_b32 s0, v254, 63
	v_readlane_b32 s1, v255, 0
	v_cndmask_b32_e64 v237, 0, 1, s[76:77]
	v_cndmask_b32_e64 v234, 0, 1, s[78:79]
	v_cndmask_b32_e64 v201, 0, 1, s[0:1]
	v_readlane_b32 s0, v255, 1
	v_readlane_b32 s1, v255, 2
	v_cndmask_b32_e64 v235, 0, 1, s[80:81]
	v_cndmask_b32_e64 v232, 0, 1, s[82:83]
	v_cndmask_b32_e64 v177, 0, 1, s[0:1]
	v_readlane_b32 s0, v255, 3
	v_readlane_b32 s1, v255, 4
	v_cndmask_b32_e64 v233, 0, 1, s[84:85]
	v_cndmask_b32_e64 v230, 0, 1, s[86:87]
	v_cndmask_b32_e64 v188, 0, 1, s[0:1]
	v_readlane_b32 s0, v255, 5
	v_readlane_b32 s1, v255, 6
	v_cndmask_b32_e64 v231, 0, 1, s[88:89]
	v_cndmask_b32_e64 v228, 0, 1, s[90:91]
	v_cndmask_b32_e64 v178, 0, 1, s[0:1]
	v_readlane_b32 s0, v255, 7
	v_readlane_b32 s1, v255, 8
	v_cndmask_b32_e64 v229, 0, 1, s[92:93]
	v_cndmask_b32_e64 v226, 0, 1, s[94:95]
	v_cndmask_b32_e64 v189, 0, 1, s[0:1]
	v_readlane_b32 s0, v255, 9
	v_readlane_b32 s1, v255, 10
	v_cndmask_b32_e64 v227, 0, 1, s[40:41]
	v_cndmask_b32_e64 v224, 0, 1, s[96:97]
	v_cndmask_b32_e64 v183, 0, 1, s[0:1]
	v_readlane_b32 s0, v255, 11
	v_readlane_b32 s1, v255, 12
	v_cndmask_b32_e64 v225, 0, 1, s[4:5]
	v_cndmask_b32_e64 v222, 0, 1, s[6:7]
	v_cndmask_b32_e64 v197, 0, 1, s[0:1]
	v_readlane_b32 s0, v255, 13
	v_readlane_b32 s1, v255, 14
	v_cndmask_b32_e64 v223, 0, 1, s[8:9]
	v_cndmask_b32_e64 v220, 0, 1, s[10:11]
	v_cndmask_b32_e64 v193, 0, 1, s[0:1]
	v_readlane_b32 s0, v255, 15
	v_readlane_b32 s1, v255, 16
	v_cndmask_b32_e64 v221, 0, 1, s[12:13]
	v_cndmask_b32_e64 v218, 0, 1, s[14:15]
	v_cndmask_b32_e64 v204, 0, 1, s[0:1]
	v_readlane_b32 s0, v255, 17
	v_readlane_b32 s1, v255, 18
	v_cndmask_b32_e64 v219, 0, 1, s[16:17]
	v_cndmask_b32_e64 v216, 0, 1, s[18:19]
	v_cndmask_b32_e64 v180, 0, 1, s[0:1]
	v_readlane_b32 s0, v255, 19
	v_readlane_b32 s1, v255, 20
	v_cndmask_b32_e64 v217, 0, 1, s[20:21]
	v_cndmask_b32_e64 v214, 0, 1, s[22:23]
	v_cndmask_b32_e64 v194, 0, 1, s[0:1]
	v_readlane_b32 s0, v255, 21
	v_readlane_b32 s1, v255, 22
	v_cndmask_b32_e64 v215, 0, 1, s[24:25]
	v_cndmask_b32_e64 v210, 0, 1, s[26:27]
	v_cndmask_b32_e64 v181, 0, 1, s[0:1]
	v_readlane_b32 s0, v255, 23
	v_readlane_b32 s1, v255, 24
	v_cndmask_b32_e64 v211, 0, 1, s[28:29]
	v_cndmask_b32_e64 v186, 0, 1, s[30:31]
	v_cndmask_b32_e64 v195, 0, 1, s[0:1]
	v_readlane_b32 s0, v255, 25
	v_readlane_b32 s1, v255, 26
	v_cndmask_b32_e64 v191, 0, 1, s[64:65]
	v_cndmask_b32_e64 v176, 0, 1, s[58:59]
	v_cndmask_b32_e64 v190, 0, 1, s[0:1]
	v_readlane_b32 s0, v255, 27
	v_readlane_b32 s1, v255, 28
	s_nop 1
	v_cndmask_b32_e64 v202, 0, 1, s[0:1]
	v_readlane_b32 s0, v255, 29
	v_readlane_b32 s1, v255, 30
	s_nop 1
	v_cndmask_b32_e64 v198, 0, 1, s[0:1]
	v_readlane_b32 s0, v255, 31
	v_readlane_b32 s1, v255, 32
	s_nop 1
	v_cndmask_b32_e64 v206, 0, 1, s[0:1]
	v_readlane_b32 s0, v255, 33
	v_readlane_b32 s1, v255, 34
	s_nop 1
	v_cndmask_b32_e64 v184, 0, 1, s[0:1]
	v_readlane_b32 s0, v255, 35
	v_readlane_b32 s1, v255, 36
	s_nop 1
	v_cndmask_b32_e64 v199, 0, 1, s[0:1]
	v_readlane_b32 s0, v255, 37
	v_readlane_b32 s1, v255, 38
	s_nop 1
	v_cndmask_b32_e64 v185, 0, 1, s[0:1]
	v_readlane_b32 s0, v255, 39
	v_readlane_b32 s1, v255, 40
	s_nop 1
	v_cndmask_b32_e64 v200, 0, 1, s[0:1]
	v_readlane_b32 s0, v255, 41
	v_readlane_b32 s1, v255, 42
	s_nop 1
	v_cndmask_b32_e64 v196, 0, 1, s[0:1]
	v_readlane_b32 s0, v255, 43
	v_readlane_b32 s1, v255, 44
	s_nop 1
	v_cndmask_b32_e64 v205, 0, 1, s[0:1]
	v_readlane_b32 s0, v255, 45
	v_readlane_b32 s1, v255, 46
	s_nop 1
	v_cndmask_b32_e64 v203, 0, 1, s[0:1]
	v_readlane_b32 s0, v255, 47
	v_readlane_b32 s1, v255, 48
	s_nop 1
	v_cndmask_b32_e64 v207, 0, 1, s[0:1]
	s_cbranch_vccnz .LBB0_848
; __device__ __forceinline__ void attn_unit(const PA& a, int l, int unit, LAS unsigned char* lds, int tid) {
;     ...
;                 if (t == 0 || t == 2) {
; #pragma unroll
;                     for (int nt = 0; nt < 8; ++nt)
; #pragma unroll
;                         for (int j = 0; j < 4; ++j) { const int qi = 16 * w + kg * 4 + j, ki = nt * 16 + fr; const bool ok = (t == 0) ? (qi <= ki) : (ki <= qi); if (!ok) s[h][nt][j] = -1e30f; } }
	v_cndmask_b32_e64 v143, v243, v242, s[38:39]
	v_and_b32_e32 v143, 1, v143
	v_cmp_eq_u32_e32 vcc, 1, v143
	v_cndmask_b32_e64 v143, v241, v240, s[38:39]
	v_mov_b32_e32 v156, s54
	v_and_b32_e32 v143, 1, v143
	v_cndmask_b32_e32 v124, v156, v124, vcc
	v_cmp_eq_u32_e32 vcc, 1, v143
	v_cndmask_b32_e64 v143, v239, v238, s[38:39]
	v_and_b32_e32 v143, 1, v143
	v_cndmask_b32_e32 v125, v253, v125, vcc
	v_cmp_eq_u32_e32 vcc, 1, v143
	v_cndmask_b32_e64 v143, v237, v236, s[38:39]
	v_and_b32_e32 v143, 1, v143
	v_cndmask_b32_e32 v126, v253, v126, vcc
	v_cmp_eq_u32_e32 vcc, 1, v143
	v_cndmask_b32_e64 v143, v235, v234, s[38:39]
	v_and_b32_e32 v143, 1, v143
	v_cndmask_b32_e32 v127, v253, v127, vcc
	v_cmp_eq_u32_e32 vcc, 1, v143
	v_cndmask_b32_e64 v143, v233, v232, s[38:39]
	v_and_b32_e32 v143, 1, v143
	v_cndmask_b32_e32 v120, v156, v120, vcc
	v_cmp_eq_u32_e32 vcc, 1, v143
	v_cndmask_b32_e64 v143, v231, v230, s[38:39]
	v_and_b32_e32 v143, 1, v143
	v_cndmask_b32_e32 v121, v253, v121, vcc
	v_cmp_eq_u32_e32 vcc, 1, v143
	v_cndmask_b32_e64 v143, v229, v228, s[38:39]
	v_and_b32_e32 v143, 1, v143
	v_cndmask_b32_e32 v122, v253, v122, vcc
	v_cmp_eq_u32_e32 vcc, 1, v143
	v_cndmask_b32_e64 v143, v227, v226, s[38:39]
	v_and_b32_e32 v143, 1, v143
	v_cndmask_b32_e32 v123, v253, v123, vcc
	v_cmp_eq_u32_e32 vcc, 1, v143
	v_cndmask_b32_e64 v143, v225, v224, s[38:39]
	v_and_b32_e32 v143, 1, v143
	v_cndmask_b32_e32 v116, v156, v116, vcc
	v_cmp_eq_u32_e32 vcc, 1, v143
	v_cndmask_b32_e64 v143, v223, v222, s[38:39]
	v_and_b32_e32 v143, 1, v143
	v_cndmask_b32_e32 v117, v253, v117, vcc
	v_cmp_eq_u32_e32 vcc, 1, v143
	v_cndmask_b32_e64 v143, v221, v220, s[38:39]
	v_and_b32_e32 v143, 1, v143
	v_cndmask_b32_e32 v118, v253, v118, vcc
	v_cmp_eq_u32_e32 vcc, 1, v143
	v_cndmask_b32_e64 v143, v219, v218, s[38:39]
	v_and_b32_e32 v143, 1, v143
	v_cndmask_b32_e32 v119, v253, v119, vcc
	v_cmp_eq_u32_e32 vcc, 1, v143
	v_cndmask_b32_e64 v143, v217, v216, s[38:39]
	v_and_b32_e32 v143, 1, v143
	v_cndmask_b32_e32 v112, v156, v112, vcc
	v_cmp_eq_u32_e32 vcc, 1, v143
	v_cndmask_b32_e64 v143, v215, v214, s[38:39]
	v_and_b32_e32 v143, 1, v143
	v_cndmask_b32_e32 v113, v253, v113, vcc
	v_cmp_eq_u32_e32 vcc, 1, v143
	v_cndmask_b32_e64 v143, v211, v210, s[38:39]
	v_and_b32_e32 v143, 1, v143
	v_cndmask_b32_e32 v114, v253, v114, vcc
	v_cmp_eq_u32_e32 vcc, 1, v143
	v_cndmask_b32_e64 v143, v191, v186, s[38:39]
	v_and_b32_e32 v143, 1, v143
	v_cndmask_b32_e32 v115, v253, v115, vcc
	v_cmp_eq_u32_e32 vcc, 1, v143
	v_cndmask_b32_e64 v143, v182, v176, s[38:39]
	v_and_b32_e32 v143, 1, v143
	v_cndmask_b32_e32 v108, v156, v108, vcc
	v_cmp_eq_u32_e32 vcc, 1, v143
	v_cndmask_b32_e64 v143, v192, v179, s[38:39]
	v_and_b32_e32 v143, 1, v143
	v_cndmask_b32_e32 v109, v253, v109, vcc
	v_cmp_eq_u32_e32 vcc, 1, v143
	v_cndmask_b32_e64 v143, v201, v187, s[38:39]
	v_and_b32_e32 v143, 1, v143
	v_cndmask_b32_e32 v110, v253, v110, vcc
	v_cmp_eq_u32_e32 vcc, 1, v143
	v_cndmask_b32_e64 v143, v188, v177, s[38:39]
	v_and_b32_e32 v143, 1, v143
	v_cndmask_b32_e32 v111, v253, v111, vcc
	v_cmp_eq_u32_e32 vcc, 1, v143
	v_cndmask_b32_e64 v143, v189, v178, s[38:39]
	v_and_b32_e32 v143, 1, v143
	v_cndmask_b32_e32 v104, v156, v104, vcc
	v_cmp_eq_u32_e32 vcc, 1, v143
	v_cndmask_b32_e64 v143, v197, v183, s[38:39]
	v_and_b32_e32 v143, 1, v143
	v_cndmask_b32_e32 v105, v253, v105, vcc
	v_cmp_eq_u32_e32 vcc, 1, v143
	v_cndmask_b32_e64 v143, v204, v193, s[38:39]
	v_and_b32_e32 v143, 1, v143
	v_cndmask_b32_e32 v106, v253, v106, vcc
	v_cmp_eq_u32_e32 vcc, 1, v143
	v_cndmask_b32_e64 v143, v194, v180, s[38:39]
	v_and_b32_e32 v143, 1, v143
	v_cndmask_b32_e32 v107, v253, v107, vcc
	v_cmp_eq_u32_e32 vcc, 1, v143
	v_cndmask_b32_e64 v143, v195, v181, s[38:39]
	v_and_b32_e32 v143, 1, v143
	v_cndmask_b32_e32 v100, v156, v100, vcc
	v_cmp_eq_u32_e32 vcc, 1, v143
	v_cndmask_b32_e64 v143, v202, v190, s[38:39]
	v_and_b32_e32 v143, 1, v143
	v_cndmask_b32_e32 v101, v253, v101, vcc
	v_cmp_eq_u32_e32 vcc, 1, v143
	v_cndmask_b32_e64 v143, v206, v198, s[38:39]
	v_and_b32_e32 v143, 1, v143
	v_cndmask_b32_e32 v102, v253, v102, vcc
	v_cmp_eq_u32_e32 vcc, 1, v143
	v_cndmask_b32_e64 v143, v199, v184, s[38:39]
	v_and_b32_e32 v143, 1, v143
	v_cndmask_b32_e32 v103, v253, v103, vcc
	v_cmp_eq_u32_e32 vcc, 1, v143
	v_cndmask_b32_e64 v143, v200, v185, s[38:39]
	v_and_b32_e32 v143, 1, v143
	v_cndmask_b32_e32 v96, v156, v96, vcc
	v_cmp_eq_u32_e32 vcc, 1, v143
	v_cndmask_b32_e64 v143, v205, v196, s[38:39]
	v_and_b32_e32 v143, 1, v143
	v_cndmask_b32_e32 v97, v253, v97, vcc
	v_cmp_eq_u32_e32 vcc, 1, v143
	v_cndmask_b32_e64 v143, v207, v203, s[38:39]
	v_and_b32_e32 v143, 1, v143
	v_cndmask_b32_e32 v98, v253, v98, vcc
	v_cmp_eq_u32_e32 vcc, 1, v143
	s_nop 1
	v_cndmask_b32_e32 v99, v253, v99, vcc
; __device__ __forceinline__ unsigned f2bf(float f) { return pk2(f, f) & 0xffffu; }
; __device__ __forceinline__ void attn_unit(const PA& a, int l, int unit, LAS unsigned char* lds, int tid) {
;     ...
;                 float alpha[4];
; #pragma unroll
;                 for (int j = 0; j < 4; ++j) { float mx = s[h][0][j];
; #pragma unroll
;                     for (int nt = 1; nt < 8; ++nt) mx = fmaxf(mx, s[h][nt][j]);
;                     mx = fmaxf(mx, shx<1>(mx)); mx = fmaxf(mx, shx<2>(mx)); mx = fmaxf(mx, shx<4>(mx)); mx = fmaxf(mx, shx<8>(mx));
;                     const float mn = fmaxf(mrow[h][j], mx); alpha[j] = __builtin_amdgcn_exp2f(mrow[h][j] - mn); mrow[h][j] = mn; lp[h][j] *= alpha[j]; }
; #pragma unroll
;                 for (int nt = 0; nt < 8; ++nt)
; #pragma unroll
;                     for (int j = 0; j < 4; ++j) { const float p = __builtin_amdgcn_exp2f(s[h][nt][j] - mrow[h][j]); lp[h][j] += p; Ph[(kg * 4 + j) * 136 + nt * 16 + fr] = (bf16)f2bf(p); }
.LBB0_848:
	v_max_f32_e32 v143, v120, v120
	v_max_f32_e32 v145, v124, v124
	v_max_f32_e32 v143, v145, v143
	v_max3_f32 v143, v143, v116, v112
	v_max3_f32 v143, v143, v108, v104
	v_max3_f32 v143, v143, v100, v96
	s_nop 1
	v_max_f32_dpp v143, v143, v143 row_ror:1 row_mask:0xf bank_mask:0xf
	v_max_f32_e32 v156, v125, v125
	v_max_f32_e32 v157, v126, v126
	s_cmp_lt_i32 s50, 2
	s_nop 1
	v_max_f32_dpp v143, v143, v143 row_ror:2 row_mask:0xf bank_mask:0xf
	s_nop 1
	v_max_f32_dpp v143, v143, v143 row_ror:4 row_mask:0xf bank_mask:0xf
	s_nop 1
	v_max_f32_dpp v143, v143, v143 row_ror:8 row_mask:0xf bank_mask:0xf
	v_max_f32_e32 v143, v175, v143
	v_max_f32_e32 v145, v121, v121
	v_max_f32_e32 v145, v156, v145
	v_max3_f32 v145, v145, v117, v113
	v_max3_f32 v145, v145, v109, v105
	v_max3_f32 v145, v145, v101, v97
	s_nop 1
	v_max_f32_dpp v145, v145, v145 row_ror:1 row_mask:0xf bank_mask:0xf
	v_sub_f32_e32 v124, v124, v143
	v_sub_f32_e32 v120, v120, v143
	v_sub_f32_e32 v116, v116, v143
	v_sub_f32_e32 v112, v112, v143
	s_nop 1
	v_max_f32_dpp v145, v145, v145 row_ror:2 row_mask:0xf bank_mask:0xf
	v_sub_f32_e32 v108, v108, v143
	v_sub_f32_e32 v104, v104, v143
	v_sub_f32_e32 v100, v100, v143
	v_sub_f32_e32 v96, v96, v143
	s_nop 1
	v_max_f32_dpp v145, v145, v145 row_ror:4 row_mask:0xf bank_mask:0xf
	s_nop 1
	v_max_f32_dpp v145, v145, v145 row_ror:8 row_mask:0xf bank_mask:0xf
	v_max_f32_e32 v145, v174, v145
	v_max_f32_e32 v156, v122, v122
	v_max_f32_e32 v156, v157, v156
	v_max3_f32 v156, v156, v118, v114
	v_max3_f32 v156, v156, v110, v106
	v_max3_f32 v156, v156, v102, v98
	s_nop 1
	v_max_f32_dpp v156, v156, v156 row_ror:1 row_mask:0xf bank_mask:0xf
	s_nop 1
	v_max_f32_dpp v156, v156, v156 row_ror:2 row_mask:0xf bank_mask:0xf
	s_nop 1
	v_max_f32_dpp v156, v156, v156 row_ror:4 row_mask:0xf bank_mask:0xf
	s_nop 1
	v_max_f32_dpp v156, v156, v156 row_ror:8 row_mask:0xf bank_mask:0xf
	v_max_f32_e32 v166, v173, v156
	v_max_f32_e32 v156, v123, v123
	v_max_f32_e32 v157, v127, v127
	v_max_f32_e32 v156, v157, v156
	v_max3_f32 v156, v156, v119, v115
	v_max3_f32 v156, v156, v111, v107
	v_max3_f32 v156, v156, v103, v99
	s_nop 1
	v_max_f32_dpp v156, v156, v156 row_ror:1 row_mask:0xf bank_mask:0xf
	s_nop 1
	v_max_f32_dpp v156, v156, v156 row_ror:2 row_mask:0xf bank_mask:0xf
	s_nop 1
	v_max_f32_dpp v156, v156, v156 row_ror:4 row_mask:0xf bank_mask:0xf
	s_nop 1
	v_max_f32_dpp v156, v156, v156 row_ror:8 row_mask:0xf bank_mask:0xf
	v_max_f32_e32 v167, v172, v156
	v_exp_f32_e32 v157, v124
	s_nop 0
	v_cvt_pk_bf16_f32 v124, v157, s0
	ds_write_b16 v158, v124 offset:35840
	v_sub_f32_e32 v124, v125, v145
	v_exp_f32_e32 v156, v124
	s_nop 0
	v_cvt_pk_bf16_f32 v124, v156, s0
	ds_write_b16 v158, v124 offset:36112
	v_sub_f32_e32 v124, v126, v166
	v_exp_f32_e32 v125, v124
	s_nop 0
	v_cvt_pk_bf16_f32 v124, v125, s0
	ds_write_b16 v158, v124 offset:36384
	v_sub_f32_e32 v124, v127, v167
	v_exp_f32_e32 v127, v120
	v_exp_f32_e32 v124, v124
	v_cvt_pk_bf16_f32 v120, v127, s0
	v_cvt_pk_bf16_f32 v126, v124, s0
	ds_write_b16 v158, v120 offset:35872
	v_sub_f32_e32 v120, v121, v145
	ds_write_b16 v158, v126 offset:36656
	v_exp_f32_e32 v126, v120
	s_nop 0
	v_cvt_pk_bf16_f32 v120, v126, s0
	ds_write_b16 v158, v120 offset:36144
	v_sub_f32_e32 v120, v122, v166
	v_exp_f32_e32 v121, v120
	s_nop 0
	v_cvt_pk_bf16_f32 v120, v121, s0
	ds_write_b16 v158, v120 offset:36416
	v_sub_f32_e32 v120, v123, v167
	v_exp_f32_e32 v123, v116
	v_exp_f32_e32 v120, v120
	v_cvt_pk_bf16_f32 v116, v123, s0
	v_cvt_pk_bf16_f32 v122, v120, s0
	ds_write_b16 v158, v116 offset:35904
	v_sub_f32_e32 v116, v117, v145
	ds_write_b16 v158, v122 offset:36688
	v_exp_f32_e32 v122, v116
	s_nop 0
	v_cvt_pk_bf16_f32 v116, v122, s0
	ds_write_b16 v158, v116 offset:36176
	v_sub_f32_e32 v116, v118, v166
	v_exp_f32_e32 v117, v116
	s_nop 0
	v_cvt_pk_bf16_f32 v116, v117, s0
	ds_write_b16 v158, v116 offset:36448
	v_sub_f32_e32 v116, v119, v167
	v_exp_f32_e32 v119, v112
	v_exp_f32_e32 v116, v116
	v_cvt_pk_bf16_f32 v112, v119, s0
	v_cvt_pk_bf16_f32 v118, v116, s0
	ds_write_b16 v158, v112 offset:35936
	v_sub_f32_e32 v112, v113, v145
	ds_write_b16 v158, v118 offset:36720
	v_exp_f32_e32 v118, v112
	s_nop 0
	v_cvt_pk_bf16_f32 v112, v118, s0
	ds_write_b16 v158, v112 offset:36208
	v_sub_f32_e32 v112, v114, v166
	v_exp_f32_e32 v113, v112
	s_nop 0
	v_cvt_pk_bf16_f32 v112, v113, s0
	ds_write_b16 v158, v112 offset:36480
	v_sub_f32_e32 v112, v115, v167
	v_exp_f32_e32 v115, v108
	v_exp_f32_e32 v112, v112
	v_cvt_pk_bf16_f32 v108, v115, s0
	v_cvt_pk_bf16_f32 v114, v112, s0
	ds_write_b16 v158, v108 offset:35968
	v_sub_f32_e32 v108, v109, v145
	ds_write_b16 v158, v114 offset:36752
	v_exp_f32_e32 v114, v108
	s_nop 0
	v_cvt_pk_bf16_f32 v108, v114, s0
	ds_write_b16 v158, v108 offset:36240
	v_sub_f32_e32 v108, v110, v166
	v_exp_f32_e32 v109, v108
	s_nop 0
	v_cvt_pk_bf16_f32 v108, v109, s0
	ds_write_b16 v158, v108 offset:36512
	v_sub_f32_e32 v108, v111, v167
	v_exp_f32_e32 v111, v104
	v_exp_f32_e32 v108, v108
	v_cvt_pk_bf16_f32 v104, v111, s0
	v_cvt_pk_bf16_f32 v110, v108, s0
	ds_write_b16 v158, v104 offset:36000
	v_sub_f32_e32 v104, v105, v145
	ds_write_b16 v158, v110 offset:36784
	v_exp_f32_e32 v110, v104
	s_nop 0
	v_cvt_pk_bf16_f32 v104, v110, s0
	ds_write_b16 v158, v104 offset:36272
	v_sub_f32_e32 v104, v106, v166
	v_exp_f32_e32 v105, v104
	s_nop 0
	v_cvt_pk_bf16_f32 v104, v105, s0
	ds_write_b16 v158, v104 offset:36544
	v_sub_f32_e32 v104, v107, v167
	v_exp_f32_e32 v107, v100
	v_exp_f32_e32 v104, v104
	v_cvt_pk_bf16_f32 v100, v107, s0
	v_cvt_pk_bf16_f32 v106, v104, s0
	ds_write_b16 v158, v100 offset:36032
	v_sub_f32_e32 v100, v101, v145
	ds_write_b16 v158, v106 offset:36816
	v_exp_f32_e32 v106, v100
	s_nop 0
	v_cvt_pk_bf16_f32 v100, v106, s0
	ds_write_b16 v158, v100 offset:36304
	v_sub_f32_e32 v100, v102, v166
	v_exp_f32_e32 v101, v100
	s_nop 0
	v_cvt_pk_bf16_f32 v100, v101, s0
	ds_write_b16 v158, v100 offset:36576
	v_sub_f32_e32 v100, v103, v167
	v_exp_f32_e32 v103, v96
	v_exp_f32_e32 v100, v100
	v_cvt_pk_bf16_f32 v96, v103, s0
	v_cvt_pk_bf16_f32 v102, v100, s0
	ds_write_b16 v158, v96 offset:36064
	v_sub_f32_e32 v96, v97, v145
	ds_write_b16 v158, v102 offset:36848
	v_exp_f32_e32 v102, v96
	s_nop 0
	v_cvt_pk_bf16_f32 v96, v102, s0
	ds_write_b16 v158, v96 offset:36336
	v_sub_f32_e32 v96, v98, v166
	v_exp_f32_e32 v97, v96
	s_nop 0
	v_cvt_pk_bf16_f32 v96, v97, s0
	ds_write_b16 v158, v96 offset:36608
	v_sub_f32_e32 v96, v99, v167
	v_exp_f32_e32 v96, v96
	s_nop 0
	v_cvt_pk_bf16_f32 v98, v96, s0
	ds_write_b16 v158, v98 offset:36880
	s_cbranch_scc1 .LBB0_850
	s_cmp_eq_u32 s50, 2
	s_cselect_b64 s[46:47], -1, 0
	s_cbranch_execz .LBB0_851
	s_branch .LBB0_852

; __device__ __forceinline__ unsigned f2bf(float f) { return pk2(f, f) & 0xffffu; }
; __device__ __forceinline__ void attn_unit(const PA& a, int l, int unit, LAS unsigned char* lds, int tid) {
;     ...
;                 float alpha[4];
; #pragma unroll
;                 for (int j = 0; j < 4; ++j) { float mx = s[h][0][j];
; #pragma unroll
;                     for (int nt = 1; nt < 8; ++nt) mx = fmaxf(mx, s[h][nt][j]);
;                     mx = fmaxf(mx, shx<1>(mx)); mx = fmaxf(mx, shx<2>(mx)); mx = fmaxf(mx, shx<4>(mx)); mx = fmaxf(mx, shx<8>(mx));
;                     const float mn = fmaxf(mrow[h][j], mx); alpha[j] = __builtin_amdgcn_exp2f(mrow[h][j] - mn); mrow[h][j] = mn; lp[h][j] *= alpha[j]; }
; #pragma unroll
;                 for (int nt = 0; nt < 8; ++nt)
; #pragma unroll
;                     for (int j = 0; j < 4; ++j) { const float p = __builtin_amdgcn_exp2f(s[h][nt][j] - mrow[h][j]); lp[h][j] += p; Ph[(kg * 4 + j) * 136 + nt * 16 + fr] = (bf16)f2bf(p); }
; #pragma unroll
;                 for (int dt = 0; dt < 4; ++dt) { o[h][dt][0] *= alpha[0]; o[h][dt][1] *= alpha[1]; o[h][dt][2] *= alpha[2]; o[h][dt][3] *= alpha[3]; }
.LBB0_854:
	v_sub_f32_e32 v98, v175, v143
	v_exp_f32_e32 v175, v98
	v_sub_f32_e32 v98, v174, v145
	v_exp_f32_e32 v174, v98
	v_sub_f32_e32 v98, v173, v166
	v_exp_f32_e32 v99, v98
	v_sub_f32_e32 v98, v172, v167
	v_pk_fma_f32 v[152:153], v[152:153], v[174:175], v[156:157]
	v_exp_f32_e32 v98, v98
	v_pk_add_f32 v[126:127], v[126:127], v[152:153]
	s_nop 0
	v_pk_add_f32 v[122:123], v[122:123], v[126:127]
	s_nop 0
	v_pk_add_f32 v[118:119], v[118:119], v[122:123]
	s_nop 0
	v_pk_add_f32 v[114:115], v[114:115], v[118:119]
	s_nop 0
	v_pk_add_f32 v[110:111], v[110:111], v[114:115]
	s_nop 0
	v_pk_add_f32 v[106:107], v[106:107], v[110:111]
	v_pk_fma_f32 v[110:111], v[150:151], v[98:99], v[124:125]
	v_pk_add_f32 v[152:153], v[102:103], v[106:107]
	v_pk_add_f32 v[110:111], v[120:121], v[110:111]
	v_mov_b32_e32 v106, v175
	v_pk_add_f32 v[110:111], v[116:117], v[110:111]
	v_mov_b32_e32 v107, v174
	v_pk_add_f32 v[110:111], v[112:113], v[110:111]
	s_nop 0
	v_pk_add_f32 v[108:109], v[108:109], v[110:111]
	s_nop 0
	v_pk_add_f32 v[104:105], v[104:105], v[108:109]
	s_nop 0
	v_pk_add_f32 v[100:101], v[100:101], v[104:105]
	v_mov_b32_e32 v104, v99
	v_pk_add_f32 v[150:151], v[96:97], v[100:101]
	v_pk_mul_f32 v[100:101], v[52:53], v[106:107]
	v_pk_mul_f32 v[52:53], v[56:57], v[106:107]
	v_max_f32_e32 v56, v88, v88
	v_max_f32_e32 v57, v92, v92
	v_max_f32_e32 v56, v57, v56
	v_max3_f32 v56, v56, v84, v80
	v_max3_f32 v56, v56, v76, v72
	v_max3_f32 v56, v56, v68, v64
	s_nop 1
	v_max_f32_dpp v56, v56, v56 row_ror:1 row_mask:0xf bank_mask:0xf
	v_mov_b32_e32 v105, v98
	v_pk_mul_f32 v[98:99], v[50:51], v[104:105]
	v_pk_mul_f32 v[102:103], v[54:55], v[104:105]
	v_pk_mul_f32 v[54:55], v[58:59], v[104:105]
	s_nop 1
	v_max_f32_dpp v56, v56, v56 row_ror:2 row_mask:0xf bank_mask:0xf
	v_pk_mul_f32 v[50:51], v[62:63], v[104:105]
	v_max_f32_e32 v58, v93, v93
	v_max_f32_e32 v59, v94, v94
	v_pk_mul_f32 v[96:97], v[48:49], v[106:107]
	s_nop 1
	v_max_f32_dpp v56, v56, v56 row_ror:4 row_mask:0xf bank_mask:0xf
	v_pk_mul_f32 v[48:49], v[60:61], v[106:107]
	v_max_f32_e32 v60, v95, v95
	s_nop 1
	v_max_f32_dpp v56, v56, v56 row_ror:8 row_mask:0xf bank_mask:0xf
	v_max_f32_e32 v104, v171, v56
	v_sub_f32_e32 v56, v171, v104
	v_exp_f32_e32 v57, v56
	v_max_f32_e32 v56, v89, v89
	v_max_f32_e32 v56, v58, v56
	v_max3_f32 v56, v56, v85, v81
	v_max3_f32 v56, v56, v77, v73
	v_max3_f32 v56, v56, v69, v65
	s_nop 1
	v_max_f32_dpp v56, v56, v56 row_ror:1 row_mask:0xf bank_mask:0xf
	v_sub_f32_e32 v88, v88, v104
	v_sub_f32_e32 v84, v84, v104
	v_sub_f32_e32 v80, v80, v104
	v_sub_f32_e32 v76, v76, v104
	s_nop 1
	v_max_f32_dpp v56, v56, v56 row_ror:2 row_mask:0xf bank_mask:0xf
	v_sub_f32_e32 v72, v72, v104
	v_sub_f32_e32 v68, v68, v104
	v_sub_f32_e32 v64, v64, v104
	v_mov_b32_e32 v171, v104
	s_nop 1
	v_max_f32_dpp v56, v56, v56 row_ror:4 row_mask:0xf bank_mask:0xf
	s_nop 1
	v_max_f32_dpp v56, v56, v56 row_ror:8 row_mask:0xf bank_mask:0xf
	v_max_f32_e32 v105, v170, v56
	v_max_f32_e32 v58, v90, v90
	v_max_f32_e32 v58, v59, v58
	v_max3_f32 v58, v58, v86, v82
	v_max3_f32 v58, v58, v78, v74
	v_max3_f32 v58, v58, v70, v66
	s_nop 1
	v_max_f32_dpp v58, v58, v58 row_ror:1 row_mask:0xf bank_mask:0xf
	v_sub_f32_e32 v56, v170, v105
	v_exp_f32_e32 v56, v56
	v_mov_b32_e32 v170, v105
	s_nop 1
	v_max_f32_dpp v58, v58, v58 row_ror:2 row_mask:0xf bank_mask:0xf
	s_nop 1
	v_max_f32_dpp v58, v58, v58 row_ror:4 row_mask:0xf bank_mask:0xf
	s_nop 1
	v_max_f32_dpp v58, v58, v58 row_ror:8 row_mask:0xf bank_mask:0xf
	v_max_f32_e32 v106, v169, v58
	v_sub_f32_e32 v58, v169, v106
	v_exp_f32_e32 v59, v58
	v_max_f32_e32 v58, v91, v91
	v_max_f32_e32 v58, v60, v58
	v_max3_f32 v58, v58, v87, v83
	v_max3_f32 v58, v58, v79, v75
	v_max3_f32 v58, v58, v71, v67
	s_nop 1
	v_max_f32_dpp v58, v58, v58 row_ror:1 row_mask:0xf bank_mask:0xf
	v_mov_b32_e32 v169, v106
	s_nop 1
	v_max_f32_dpp v58, v58, v58 row_ror:2 row_mask:0xf bank_mask:0xf
	s_nop 1
	v_max_f32_dpp v58, v58, v58 row_ror:4 row_mask:0xf bank_mask:0xf
	s_nop 1
	v_max_f32_dpp v58, v58, v58 row_ror:8 row_mask:0xf bank_mask:0xf
	v_max_f32_e32 v107, v168, v58
	v_sub_f32_e32 v60, v92, v104
	v_exp_f32_e32 v63, v60
	v_sub_f32_e32 v58, v168, v107
	v_exp_f32_e32 v58, v58
	v_mov_b32_e32 v168, v107
	v_cvt_pk_bf16_f32 v60, v63, s0
	ds_write_b16 v158, v60 offset:40192
	v_sub_f32_e32 v60, v93, v105
	v_exp_f32_e32 v62, v60
	v_exp_f32_e32 v93, v88
	v_cvt_pk_bf16_f32 v60, v62, s0
	ds_write_b16 v158, v60 offset:40464
	v_sub_f32_e32 v60, v94, v106
	v_exp_f32_e32 v61, v60
	v_cvt_pk_bf16_f32 v88, v93, s0
	ds_write_b16 v158, v88 offset:40224
	v_sub_f32_e32 v88, v89, v105
	v_cvt_pk_bf16_f32 v60, v61, s0
	ds_write_b16 v158, v60 offset:40736
	v_sub_f32_e32 v60, v95, v107
	v_exp_f32_e32 v60, v60
	v_pk_fma_f32 v[62:63], v[148:149], v[56:57], v[62:63]
	v_cvt_pk_bf16_f32 v92, v60, s0
	ds_write_b16 v158, v92 offset:41008
	v_exp_f32_e32 v92, v88
	v_pk_fma_f32 v[60:61], v[146:147], v[58:59], v[60:61]
	v_cvt_pk_bf16_f32 v88, v92, s0
	ds_write_b16 v158, v88 offset:40496
	v_sub_f32_e32 v88, v90, v106
	v_exp_f32_e32 v89, v88
	v_pk_add_f32 v[62:63], v[92:93], v[62:63]
	v_cvt_pk_bf16_f32 v88, v89, s0
	ds_write_b16 v158, v88 offset:40768
	v_sub_f32_e32 v88, v91, v107
	v_exp_f32_e32 v91, v84
	v_exp_f32_e32 v88, v88
	v_cvt_pk_bf16_f32 v84, v91, s0
	v_cvt_pk_bf16_f32 v90, v88, s0
	ds_write_b16 v158, v84 offset:40256
	v_sub_f32_e32 v84, v85, v105
	ds_write_b16 v158, v90 offset:41040
	v_exp_f32_e32 v90, v84
	v_pk_add_f32 v[60:61], v[88:89], v[60:61]
	v_cvt_pk_bf16_f32 v84, v90, s0
	ds_write_b16 v158, v84 offset:40528
	v_sub_f32_e32 v84, v86, v106
	v_exp_f32_e32 v85, v84
	v_pk_add_f32 v[62:63], v[90:91], v[62:63]
	v_cvt_pk_bf16_f32 v84, v85, s0
; #define LAS __attribute__((address_space(3)))
; __device__ __forceinline__ unsigned f2bf(float f) { return pk2(f, f) & 0xffffu; }
; #define MFMA16(a, b, c) __builtin_amdgcn_mfma_f32_16x16x32_bf16((a), (b), (c), 0, 0, 0)
; #define WAVE_LDS_SYNC() asm volatile("s_waitcnt lgkmcnt(0)" ::: "memory")
; __device__ __forceinline__ void attn_unit(const PA& a, int l, int unit, LAS unsigned char* lds, int tid) {
;     ...
;                 for (int nt = 0; nt < 8; ++nt)
; #pragma unroll
;                     for (int j = 0; j < 4; ++j) { const float p = __builtin_amdgcn_exp2f(s[h][nt][j] - mrow[h][j]); lp[h][j] += p; Ph[(kg * 4 + j) * 136 + nt * 16 + fr] = (bf16)f2bf(p); }
; #pragma unroll
;                 for (int dt = 0; dt < 4; ++dt) { o[h][dt][0] *= alpha[0]; o[h][dt][1] *= alpha[1]; o[h][dt][2] *= alpha[2]; o[h][dt][3] *= alpha[3]; }
;             }
;             WAVE_LDS_SYNC();
; #pragma unroll
;             for (int ks = 0; ks < 4; ++ks) { const bf16x8 pa0 = *(const LAS bf16x8*)(P + fr * 136 + ks * 32 + kg * 8), pa1 = *(const LAS bf16x8*)(P + 2176 + fr * 136 + ks * 32 + kg * 8);
; #pragma unroll
;                 for (int dt = 0; dt < 4; ++dt) { const bf16x8 vb = *(const LAS bf16x8*)(Vt + (dt * 16 + fr) * 136 + ks * 32 + kg * 8); o[0][dt] = MFMA16(pa0, vb, o[0][dt]); o[1][dt] = MFMA16(pa1, vb, o[1][dt]); } }
;             WAVE_LDS_SYNC();
	ds_write_b16 v158, v84 offset:40800
	v_sub_f32_e32 v84, v87, v107
	v_exp_f32_e32 v87, v80
	v_exp_f32_e32 v84, v84
	v_cvt_pk_bf16_f32 v80, v87, s0
	v_cvt_pk_bf16_f32 v86, v84, s0
	ds_write_b16 v158, v80 offset:40288
	v_sub_f32_e32 v80, v81, v105
	ds_write_b16 v158, v86 offset:41072
	v_exp_f32_e32 v86, v80
	v_pk_add_f32 v[60:61], v[84:85], v[60:61]
	v_cvt_pk_bf16_f32 v80, v86, s0
	ds_write_b16 v158, v80 offset:40560
	v_sub_f32_e32 v80, v82, v106
	v_exp_f32_e32 v81, v80
	v_pk_add_f32 v[62:63], v[86:87], v[62:63]
	v_cvt_pk_bf16_f32 v80, v81, s0
	ds_write_b16 v158, v80 offset:40832
	v_sub_f32_e32 v80, v83, v107
	v_exp_f32_e32 v83, v76
	v_exp_f32_e32 v80, v80
	v_cvt_pk_bf16_f32 v76, v83, s0
	v_cvt_pk_bf16_f32 v82, v80, s0
	ds_write_b16 v158, v76 offset:40320
	v_sub_f32_e32 v76, v77, v105
	ds_write_b16 v158, v82 offset:41104
	v_exp_f32_e32 v82, v76
	v_pk_add_f32 v[60:61], v[80:81], v[60:61]
	v_cvt_pk_bf16_f32 v76, v82, s0
	ds_write_b16 v158, v76 offset:40592
	v_sub_f32_e32 v76, v78, v106
	v_exp_f32_e32 v77, v76
	v_pk_add_f32 v[62:63], v[82:83], v[62:63]
	v_cvt_pk_bf16_f32 v76, v77, s0
	ds_write_b16 v158, v76 offset:40864
	v_sub_f32_e32 v76, v79, v107
	v_exp_f32_e32 v79, v72
	v_exp_f32_e32 v76, v76
	v_cvt_pk_bf16_f32 v72, v79, s0
	v_cvt_pk_bf16_f32 v78, v76, s0
	ds_write_b16 v158, v72 offset:40352
	v_sub_f32_e32 v72, v73, v105
	ds_write_b16 v158, v78 offset:41136
	v_exp_f32_e32 v78, v72
	v_pk_add_f32 v[60:61], v[76:77], v[60:61]
	v_cvt_pk_bf16_f32 v72, v78, s0
	ds_write_b16 v158, v72 offset:40624
	v_sub_f32_e32 v72, v74, v106
	v_exp_f32_e32 v73, v72
	v_pk_add_f32 v[62:63], v[78:79], v[62:63]
	v_cvt_pk_bf16_f32 v72, v73, s0
	ds_write_b16 v158, v72 offset:40896
	v_sub_f32_e32 v72, v75, v107
	v_exp_f32_e32 v75, v68
	v_exp_f32_e32 v72, v72
	v_cvt_pk_bf16_f32 v68, v75, s0
	v_cvt_pk_bf16_f32 v74, v72, s0
	ds_write_b16 v158, v68 offset:40384
	v_sub_f32_e32 v68, v69, v105
	ds_write_b16 v158, v74 offset:41168
	v_exp_f32_e32 v74, v68
	v_pk_add_f32 v[60:61], v[72:73], v[60:61]
	v_cvt_pk_bf16_f32 v68, v74, s0
	ds_write_b16 v158, v68 offset:40656
	v_sub_f32_e32 v68, v70, v106
	v_exp_f32_e32 v69, v68
	v_pk_add_f32 v[62:63], v[74:75], v[62:63]
	v_cvt_pk_bf16_f32 v68, v69, s0
	ds_write_b16 v158, v68 offset:40928
	v_sub_f32_e32 v68, v71, v107
	v_exp_f32_e32 v68, v68
	s_nop 0
	v_pk_add_f32 v[60:61], v[68:69], v[60:61]
	v_exp_f32_e32 v69, v64
	v_cvt_pk_bf16_f32 v68, v68, s0
	ds_write_b16 v158, v68 offset:41200
	v_cvt_pk_bf16_f32 v64, v69, s0
	ds_write_b16 v158, v64 offset:40416
	v_sub_f32_e32 v64, v65, v105
	v_exp_f32_e32 v68, v64
	s_nop 0
	v_pk_add_f32 v[148:149], v[68:69], v[62:63]
	v_cvt_pk_bf16_f32 v62, v68, s0
	ds_write_b16 v158, v62 offset:40688
	v_sub_f32_e32 v62, v66, v106
	v_exp_f32_e32 v63, v62
	s_nop 0
	v_cvt_pk_bf16_f32 v62, v63, s0
	ds_write_b16 v158, v62 offset:40960
	v_sub_f32_e32 v62, v67, v107
	v_exp_f32_e32 v62, v62
	s_nop 0
	v_pk_add_f32 v[146:147], v[62:63], v[60:61]
	v_cvt_pk_bf16_f32 v60, v62, s0
	ds_write_b16 v158, v60 offset:41232
	v_mov_b32_e32 v60, v59
	v_mov_b32_e32 v61, v58
	v_mov_b32_e32 v58, v57
	v_mov_b32_e32 v59, v56
	s_waitcnt lgkmcnt(0)
	v_pk_mul_f32 v[2:3], v[2:3], v[60:61]
	v_pk_mul_f32 v[0:1], v[0:1], v[58:59]
	v_pk_mul_f32 v[6:7], v[6:7], v[60:61]
	v_pk_mul_f32 v[4:5], v[4:5], v[58:59]
	v_pk_mul_f32 v[10:11], v[10:11], v[60:61]
	v_pk_mul_f32 v[8:9], v[8:9], v[58:59]
	v_pk_mul_f32 v[14:15], v[14:15], v[60:61]
	v_pk_mul_f32 v[12:13], v[12:13], v[58:59]
	ds_read_b128 v[56:59], v137 offset:35840
	ds_read_b128 v[60:63], v141 offset:40192
	ds_read_b128 v[64:67], v164 offset:18432
	s_waitcnt lgkmcnt(0)
	v_mfma_f32_16x16x32_bf16 v[68:71], v[56:59], v[64:67], v[96:99]
	v_mfma_f32_16x16x32_bf16 v[0:3], v[60:63], v[64:67], v[0:3]
	ds_read_b128 v[64:67], v164 offset:22784
	s_waitcnt lgkmcnt(0)
	v_mfma_f32_16x16x32_bf16 v[72:75], v[56:59], v[64:67], v[100:103]
	v_mfma_f32_16x16x32_bf16 v[4:7], v[60:63], v[64:67], v[4:7]
	ds_read_b128 v[64:67], v164 offset:27136
	s_waitcnt lgkmcnt(0)
	v_mfma_f32_16x16x32_bf16 v[52:55], v[56:59], v[64:67], v[52:55]
	v_mfma_f32_16x16x32_bf16 v[8:11], v[60:63], v[64:67], v[8:11]
	ds_read_b128 v[64:67], v164 offset:31488
	s_waitcnt lgkmcnt(0)
	v_mfma_f32_16x16x32_bf16 v[48:51], v[56:59], v[64:67], v[48:51]
	v_mfma_f32_16x16x32_bf16 v[12:15], v[60:63], v[64:67], v[12:15]
	ds_read_b128 v[56:59], v137 offset:35904
	ds_read_b128 v[60:63], v141 offset:40256
	ds_read_b128 v[64:67], v164 offset:18496
	s_waitcnt lgkmcnt(0)
	v_mfma_f32_16x16x32_bf16 v[68:71], v[56:59], v[64:67], v[68:71]
	v_mfma_f32_16x16x32_bf16 v[0:3], v[60:63], v[64:67], v[0:3]
	ds_read_b128 v[64:67], v164 offset:22848
	s_waitcnt lgkmcnt(0)
	v_mfma_f32_16x16x32_bf16 v[72:75], v[56:59], v[64:67], v[72:75]
	v_mfma_f32_16x16x32_bf16 v[4:7], v[60:63], v[64:67], v[4:7]
	ds_read_b128 v[64:67], v164 offset:27200
	s_waitcnt lgkmcnt(0)
	v_mfma_f32_16x16x32_bf16 v[52:55], v[56:59], v[64:67], v[52:55]
	v_mfma_f32_16x16x32_bf16 v[8:11], v[60:63], v[64:67], v[8:11]
	ds_read_b128 v[64:67], v164 offset:31552
	s_waitcnt lgkmcnt(0)
	v_mfma_f32_16x16x32_bf16 v[48:51], v[56:59], v[64:67], v[48:51]
	v_mfma_f32_16x16x32_bf16 v[12:15], v[60:63], v[64:67], v[12:15]
	ds_read_b128 v[56:59], v137 offset:35968
	ds_read_b128 v[64:67], v141 offset:40320
	ds_read_b128 v[60:63], v164 offset:18560
	s_waitcnt lgkmcnt(0)
	v_mfma_f32_16x16x32_bf16 v[68:71], v[56:59], v[60:63], v[68:71]
	v_mfma_f32_16x16x32_bf16 v[0:3], v[64:67], v[60:63], v[0:3]
	ds_read_b128 v[60:63], v164 offset:22912
	s_waitcnt lgkmcnt(0)
	v_mfma_f32_16x16x32_bf16 v[72:75], v[56:59], v[60:63], v[72:75]
	v_mfma_f32_16x16x32_bf16 v[4:7], v[64:67], v[60:63], v[4:7]
	ds_read_b128 v[60:63], v164 offset:27264
	s_waitcnt lgkmcnt(0)
	v_mfma_f32_16x16x32_bf16 v[76:79], v[56:59], v[60:63], v[52:55]
	s_nop 2
	ds_read_b128 v[52:55], v164 offset:31616
	v_mfma_f32_16x16x32_bf16 v[8:11], v[64:67], v[60:63], v[8:11]
	s_waitcnt lgkmcnt(0)
	v_mfma_f32_16x16x32_bf16 v[60:63], v[56:59], v[52:55], v[48:51]
	v_mfma_f32_16x16x32_bf16 v[12:15], v[64:67], v[52:55], v[12:15]
	ds_read_b128 v[64:67], v137 offset:36032
	ds_read_b128 v[80:83], v141 offset:40384
	ds_read_b128 v[52:55], v164 offset:18624
	ds_read_b128 v[56:59], v164 offset:22976
	s_waitcnt lgkmcnt(1)
	v_mfma_f32_16x16x32_bf16 v[48:51], v[64:67], v[52:55], v[68:71]
	s_nop 2
	ds_read_b128 v[68:71], v164 offset:27328
	v_mfma_f32_16x16x32_bf16 v[0:3], v[80:83], v[52:55], v[0:3]
	s_waitcnt lgkmcnt(1)
	v_mfma_f32_16x16x32_bf16 v[52:55], v[64:67], v[56:59], v[72:75]
	v_mfma_f32_16x16x32_bf16 v[4:7], v[80:83], v[56:59], v[4:7]
	s_waitcnt lgkmcnt(0)
	v_mfma_f32_16x16x32_bf16 v[56:59], v[64:67], v[68:71], v[76:79]
	v_mfma_f32_16x16x32_bf16 v[8:11], v[80:83], v[68:71], v[8:11]
	ds_read_b128 v[68:71], v164 offset:31680
	s_waitcnt lgkmcnt(0)
	s_waitcnt lgkmcnt(0)
	v_mfma_f32_16x16x32_bf16 v[60:63], v[64:67], v[68:71], v[60:63]
	v_mfma_f32_16x16x32_bf16 v[12:15], v[80:83], v[68:71], v[12:15]
	s_cmp_lt_u32 s50, 4
	s_cbranch_scc1 .LBB0_835
	s_branch .LBB0_824
